# pool mixer: next item's gate loads moved from the item-top prefetch burst to in front of the two MFMA clusters
# baseline (speedup 1.0000x reference)
.LBB0_919:
	s_or_b64 exec, exec, s[6:7]
	ds_read_b128 v[160:163], v154
	ds_read_b128 v[164:167], v155
	ds_read_b128 v[168:171], v159
	v_mov_b32_e32 v197, v196
	v_mov_b32_e32 v193, v177
	s_add_i32 s8, s8, s5
	s_waitcnt lgkmcnt(0)
	v_lshlrev_b32_e32 v154, 16, v160
	v_and_b32_e32 v155, 0xffff0000, v160
	v_add_f32_e32 v154, v222, v154
	v_add_f32_e32 v155, v223, v155
	v_lshlrev_b32_e32 v158, 16, v164
	v_and_b32_e32 v159, 0xffff0000, v164
	v_add_f32_e32 v154, v154, v158
	v_add_f32_e32 v155, v155, v159
	v_lshlrev_b32_e32 v158, 16, v168
	v_and_b32_e32 v159, 0xffff0000, v168
	v_add_f32_e32 v154, v154, v158
	v_add_f32_e32 v155, v155, v159
	v_lshlrev_b32_e32 v158, 16, v161
	v_and_b32_e32 v159, 0xffff0000, v161
	v_add_f32_e32 v148, v148, v158
	v_add_f32_e32 v149, v149, v159
	v_lshlrev_b32_e32 v158, 16, v165
	v_and_b32_e32 v159, 0xffff0000, v165
	v_add_f32_e32 v148, v148, v158
	v_add_f32_e32 v149, v149, v159
	v_lshlrev_b32_e32 v158, 16, v169
	v_and_b32_e32 v159, 0xffff0000, v169
	v_add_f32_e32 v148, v148, v158
	v_add_f32_e32 v149, v149, v159
	v_fma_f32 v154, v196, v154, -v206
	v_fma_f32 v155, v197, v155, -v207
	v_fma_f32 v144, v196, v148, -v144
	v_fma_f32 v145, v197, v149, -v145
	v_cvt_pk_bf16_f32 v154, v154, v155
	v_cvt_pk_bf16_f32 v155, v144, v145
	v_lshlrev_b32_e32 v144, 16, v162
	v_and_b32_e32 v145, 0xffff0000, v162
	v_add_f32_e32 v144, v156, v144
	v_add_f32_e32 v145, v157, v145
	v_lshlrev_b32_e32 v148, 16, v166
	v_and_b32_e32 v149, 0xffff0000, v166
	v_add_f32_e32 v144, v144, v148
	v_add_f32_e32 v145, v145, v149
	v_lshlrev_b32_e32 v148, 16, v170
	v_and_b32_e32 v149, 0xffff0000, v170
	v_add_f32_e32 v144, v144, v148
	v_add_f32_e32 v145, v145, v149
	v_lshlrev_b32_e32 v148, 16, v167
	v_fma_f32 v144, v196, v144, -v152
	v_fma_f32 v145, v197, v145, -v153
	v_and_b32_e32 v149, 0xffff0000, v167
	v_cvt_pk_bf16_f32 v156, v144, v145
	v_lshlrev_b32_e32 v144, 16, v163
	v_and_b32_e32 v145, 0xffff0000, v163
	v_add_f32_e32 v144, v150, v144
	v_add_f32_e32 v145, v151, v145
	v_lshlrev_b32_e32 v152, 16, v171
	v_add_f32_e32 v144, v144, v148
	v_add_f32_e32 v145, v145, v149
	v_and_b32_e32 v153, 0xffff0000, v171
	global_load_dwordx4 v[132:135], v[136:137], off offset:512
	global_load_dwordx4 v[136:139], v[136:137], off offset:576
	v_mfma_f32_16x16x32_bf16 v[148:151], v[48:51], v[140:143], 0
	v_add_f32_e64 v144, v144, v152
	v_add_f32_e64 v145, v145, v153
	v_lshl_add_u64 v[152:153], v[194:195], 0, v[192:193]
	v_fma_f32 v144, v196, v144, -v146
	v_fma_f32 v145, v197, v145, -v147
	v_mfma_f32_16x16x32_bf16 v[158:161], v[72:75], v[140:143], 0
	v_cvt_pk_bf16_f32 v157, v144, v145
	s_and_b64 vcc, exec, s[0:1]
	s_mov_b32 s6, s9
	v_mfma_f32_16x16x32_bf16 v[144:147], v[52:55], v[154:157], v[148:151]
	v_mfma_f32_16x16x32_bf16 v[148:151], v[64:67], v[140:143], 0
	v_mfma_f32_16x16x32_bf16 v[140:143], v[88:91], v[140:143], 0
	s_nop 5
	v_mul_f32_e64 v144, v60, v144
	v_mul_f32_e64 v145, v61, v145
	v_mul_f32_e32 v146, v62, v146
	v_mul_f32_e32 v147, v63, v147
	v_mfma_f32_16x16x32_bf16 v[148:151], v[68:71], v[154:157], v[148:151]
	v_mfma_f32_16x16x32_bf16 v[158:161], v[76:79], v[154:157], v[158:161]
	v_mfma_f32_16x16x32_bf16 v[140:143], v[92:95], v[154:157], v[140:143]
	v_lshlrev_b32_e32 v154, 16, v120
	v_and_b32_e32 v155, 0xffff0000, v120
	v_mul_f32_e32 v144, v144, v154
	v_mul_f32_e32 v145, v145, v155
	s_nop 0
	v_cvt_pk_bf16_f32 v120, v144, v145
	v_lshlrev_b32_e32 v144, 16, v121
	v_and_b32_e32 v145, 0xffff0000, v121
	v_mul_f32_e32 v144, v146, v144
	v_mul_f32_e32 v145, v147, v145
	v_mul_f32_e32 v146, v56, v148
	v_mul_f32_e32 v147, v57, v149
	v_lshlrev_b32_e32 v148, 16, v122
	v_and_b32_e32 v149, 0xffff0000, v122
	v_mul_f32_e32 v146, v146, v148
	v_mul_f32_e32 v147, v147, v149
	v_cvt_pk_bf16_f32 v121, v144, v145
	v_mul_f32_e32 v144, v58, v150
	v_mul_f32_e32 v145, v59, v151
	v_cvt_pk_bf16_f32 v122, v146, v147
	v_lshlrev_b32_e32 v146, 16, v123
	v_and_b32_e32 v147, 0xffff0000, v123
	v_mul_f32_e32 v144, v144, v146
	v_mul_f32_e32 v145, v145, v147
	s_nop 0
	v_cvt_pk_bf16_f32 v123, v144, v145
	global_store_dwordx4 v[152:153], v[120:123], off
	v_lshlrev_b32_e32 v144, 16, v112
	v_and_b32_e32 v145, 0xffff0000, v112
	v_mul_f32_e32 v122, v84, v158
	v_mul_f32_e32 v123, v85, v159
	v_mul_f32_e32 v120, v86, v160
	v_mul_f32_e32 v121, v87, v161
	v_mul_f32_e32 v122, v122, v144
	v_mul_f32_e32 v123, v123, v145
	s_waitcnt vmcnt(6)
	v_mov_b64_e32 v[146:147], v[126:127]
	v_cvt_pk_bf16_f32 v112, v122, v123
	v_lshlrev_b32_e32 v122, 16, v113
	v_and_b32_e32 v123, 0xffff0000, v113
	v_mul_f32_e32 v120, v120, v122
	v_mul_f32_e32 v121, v121, v123
	v_mul_f32_e32 v122, v80, v140
	v_mul_f32_e32 v123, v81, v141
	v_lshlrev_b32_e32 v140, 16, v114
	v_and_b32_e32 v141, 0xffff0000, v114
	v_mul_f32_e32 v122, v122, v140
	v_mul_f32_e32 v123, v123, v141
	v_cvt_pk_bf16_f32 v113, v120, v121
	v_mul_f32_e32 v120, v82, v142
	v_mul_f32_e32 v121, v83, v143
	v_cvt_pk_bf16_f32 v114, v122, v123
	v_lshlrev_b32_e32 v122, 16, v115
	v_and_b32_e32 v123, 0xffff0000, v115
	v_mul_f32_e32 v120, v120, v122
	v_mul_f32_e32 v121, v121, v123
	s_waitcnt vmcnt(5)
	v_mov_b64_e32 v[142:143], v[130:131]
	v_cvt_pk_bf16_f32 v115, v120, v121
	global_store_dwordx4 v[152:153], v[112:115], off offset:64
	s_waitcnt vmcnt(3)
	v_mov_b64_e32 v[120:121], v[132:133]
	v_mov_b64_e32 v[144:145], v[124:125]
	s_waitcnt vmcnt(2)
	v_mov_b64_e32 v[112:113], v[136:137]
	v_mov_b64_e32 v[140:141], v[128:129]
	v_mov_b64_e32 v[122:123], v[134:135]
	v_mov_b64_e32 v[114:115], v[138:139]
	s_cbranch_vccnz .LBB0_938

.LBB0_930:
	s_or_b64 exec, exec, s[2:3]
	v_or_b32_e32 v124, s7, v188
	v_mad_i64_i32 v[132:133], s[2:3], v124, s33, v[190:191]
	v_lshl_add_u64 v[128:129], v[132:133], 0, v[184:185]
	v_lshl_add_u64 v[136:137], v[132:133], 0, v[182:183]
	s_cmpk_lt_i32 s6, 0x200
	s_cselect_b32 s2, s89, 0x1000
	s_add_i32 s3, s2, -1
	s_waitcnt lgkmcnt(0)
	s_barrier
	s_and_b32 s3, s3, s8
	v_or_b32_e32 v158, s3, v188
	v_add_u32_e32 v159, v243, v178
	s_and_saveexec_b64 s[6:7], s[36:37]
	s_xor_b64 s[6:7], exec, s[6:7]
	s_cbranch_execz .LBB0_932
	v_add_u32_e32 v148, 2, v158
	v_min_u32_e32 v148, s2, v148
	v_sub_u32_e64 v149, v158, 2 clamp
	v_sub_u32_e32 v148, v148, v149
	v_cvt_f32_i32_e32 v148, v148
	v_div_scale_f32 v149, s[10:11], v148, v148, 1.0
	v_rcp_f32_e32 v150, v149
	s_nop 0
	v_fma_f32 v151, -v149, v150, 1.0
	v_fmac_f32_e32 v150, v151, v150
	v_div_scale_f32 v151, vcc, 1.0, v148, 1.0
	v_mul_f32_e32 v152, v151, v150
	v_fma_f32 v153, -v149, v152, v151
	v_fmac_f32_e32 v152, v153, v150
	v_fma_f32 v149, -v149, v152, v151
	v_div_fmas_f32 v149, v149, v150, v152
	v_div_fixup_f32 v156, v149, v148, 1.0
	ds_read_b128 v[148:151], v159 offset:3296
	ds_read_b128 v[152:155], v159 offset:3824
	ds_read_b128 v[160:163], v159 offset:4352
	ds_read_b128 v[164:167], v159 offset:4880
	s_waitcnt lgkmcnt(0)
	v_lshlrev_b32_e32 v168, 16, v148
	v_and_b32_e32 v169, 0xffff0000, v148
	v_lshlrev_b32_e32 v170, 16, v152
	v_and_b32_e32 v171, 0xffff0000, v152
	v_add_f32_e32 v168, v168, v170
	v_add_f32_e32 v169, v169, v171
	v_lshlrev_b32_e32 v170, 16, v160
	v_and_b32_e32 v171, 0xffff0000, v160
	v_add_f32_e32 v168, v168, v170
	v_add_f32_e32 v169, v169, v171
	v_lshlrev_b32_e32 v172, 16, v164
	v_and_b32_e32 v173, 0xffff0000, v164
	v_add_f32_e32 v168, v168, v172
	v_add_f32_e32 v169, v169, v173
	v_lshlrev_b32_e32 v152, 16, v153
	v_fma_f32 v168, v156, v168, -v170
	v_fma_f32 v169, v156, v169, -v171
	v_cvt_pk_bf16_f32 v148, v168, v169
	v_lshlrev_b32_e32 v168, 16, v149
	v_and_b32_e32 v169, 0xffff0000, v149
	v_and_b32_e32 v153, 0xffff0000, v153
	v_add_f32_e32 v152, v168, v152
	v_add_f32_e32 v153, v169, v153
	v_lshlrev_b32_e32 v160, 16, v161
	v_and_b32_e32 v161, 0xffff0000, v161
	v_add_f32_e32 v152, v152, v160
	v_add_f32_e32 v153, v153, v161
	v_lshlrev_b32_e32 v164, 16, v165
	v_and_b32_e32 v165, 0xffff0000, v165
	v_add_f32_e32 v152, v152, v164
	v_add_f32_e32 v153, v153, v165
	v_lshlrev_b32_e32 v164, 16, v166
	v_fma_f32 v152, v156, v152, -v160
	v_fma_f32 v153, v156, v153, -v161
	v_cvt_pk_bf16_f32 v149, v152, v153
	v_lshlrev_b32_e32 v152, 16, v150
	v_and_b32_e32 v153, 0xffff0000, v150
	v_lshlrev_b32_e32 v160, 16, v154
	v_and_b32_e32 v161, 0xffff0000, v154
	v_add_f32_e32 v152, v152, v160
	v_add_f32_e32 v153, v153, v161
	v_lshlrev_b32_e32 v160, 16, v162
	v_and_b32_e32 v161, 0xffff0000, v162
	v_add_f32_e32 v152, v152, v160
	v_add_f32_e32 v153, v153, v161
	v_and_b32_e32 v165, 0xffff0000, v166
	v_add_f32_e32 v152, v152, v164
	v_add_f32_e32 v153, v153, v165
	v_lshlrev_b32_e32 v154, 16, v155
	v_fma_f32 v152, v156, v152, -v160
	v_fma_f32 v153, v156, v153, -v161
	v_cvt_pk_bf16_f32 v150, v152, v153
	v_lshlrev_b32_e32 v152, 16, v151
	v_and_b32_e32 v153, 0xffff0000, v151
	v_and_b32_e32 v155, 0xffff0000, v155
	v_add_f32_e32 v152, v152, v154
	v_add_f32_e32 v153, v153, v155
	v_lshlrev_b32_e32 v154, 16, v163
	v_and_b32_e32 v155, 0xffff0000, v163
	v_add_f32_e32 v152, v152, v154
	v_add_f32_e32 v153, v153, v155
	v_lshlrev_b32_e32 v160, 16, v167
	v_and_b32_e32 v161, 0xffff0000, v167
	v_add_f32_e32 v152, v152, v160
	v_add_f32_e32 v153, v153, v161
	s_nop 0
	v_fma_f32 v152, v156, v152, -v154
	v_fma_f32 v153, v156, v153, -v155
	v_cvt_pk_bf16_f32 v151, v152, v153
	ds_read_b128 v[152:155], v159 offset:3360
	ds_read_b128 v[160:163], v159 offset:3888
	ds_read_b128 v[164:167], v159 offset:4416
	ds_read_b128 v[168:171], v159 offset:4944
	s_waitcnt lgkmcnt(3)
	v_lshlrev_b32_e32 v172, 16, v152
	v_and_b32_e32 v173, 0xffff0000, v152
	v_add_f32_e32 v173, 0, v173
	s_waitcnt lgkmcnt(2)
	v_lshlrev_b32_e32 v174, 16, v160
	v_and_b32_e32 v175, 0xffff0000, v160
	v_add_f32_e32 v172, v172, v174
	v_add_f32_e32 v173, v173, v175
	s_waitcnt lgkmcnt(1)
	v_lshlrev_b32_e32 v174, 16, v164
	v_and_b32_e32 v175, 0xffff0000, v164
	v_add_f32_e32 v172, v172, v174
	v_add_f32_e32 v173, v173, v175
	s_waitcnt lgkmcnt(0)
	v_lshlrev_b32_e32 v194, 16, v168
	v_and_b32_e32 v195, 0xffff0000, v168
	v_add_f32_e32 v172, v172, v194
	v_add_f32_e32 v173, v173, v195
	v_lshlrev_b32_e32 v160, 16, v161
	v_fma_f32 v172, v156, v172, -v174
	v_fma_f32 v173, v156, v173, -v175
	v_cvt_pk_bf16_f32 v152, v172, v173
	v_lshlrev_b32_e32 v172, 16, v153
	v_and_b32_e32 v173, 0xffff0000, v153
	v_and_b32_e32 v161, 0xffff0000, v161
	v_add_f32_e32 v160, v172, v160
	v_add_f32_e32 v161, v173, v161
	v_lshlrev_b32_e32 v164, 16, v165
	v_and_b32_e32 v165, 0xffff0000, v165
	v_add_f32_e32 v160, v160, v164
	v_add_f32_e32 v161, v161, v165
	v_lshlrev_b32_e32 v168, 16, v169
	v_and_b32_e32 v169, 0xffff0000, v169
	v_add_f32_e32 v160, v160, v168
	v_add_f32_e32 v161, v161, v169
	v_lshlrev_b32_e32 v168, 16, v170
	v_fma_f32 v160, v156, v160, -v164
	v_fma_f32 v161, v156, v161, -v165
	v_cvt_pk_bf16_f32 v153, v160, v161
	v_lshlrev_b32_e32 v160, 16, v154
	v_and_b32_e32 v161, 0xffff0000, v154
	v_lshlrev_b32_e32 v164, 16, v162
	v_and_b32_e32 v165, 0xffff0000, v162
	v_add_f32_e32 v160, v160, v164
	v_add_f32_e32 v161, v161, v165
	v_lshlrev_b32_e32 v164, 16, v166
	v_and_b32_e32 v165, 0xffff0000, v166
	v_add_f32_e32 v160, v160, v164
	v_add_f32_e32 v161, v161, v165
	v_and_b32_e32 v169, 0xffff0000, v170
	v_add_f32_e32 v160, v160, v168
	v_add_f32_e32 v161, v161, v169
	v_lshlrev_b32_e32 v162, 16, v163
	v_fma_f32 v160, v156, v160, -v164
	v_fma_f32 v161, v156, v161, -v165
	v_cvt_pk_bf16_f32 v154, v160, v161
	v_lshlrev_b32_e32 v160, 16, v155
	v_and_b32_e32 v161, 0xffff0000, v155
	v_and_b32_e32 v163, 0xffff0000, v163
	v_add_f32_e32 v160, v160, v162
	v_add_f32_e32 v161, v161, v163
	v_lshlrev_b32_e32 v162, 16, v167
	v_and_b32_e32 v163, 0xffff0000, v167
	v_add_f32_e32 v160, v160, v162
	v_add_f32_e32 v161, v161, v163
	v_lshlrev_b32_e32 v164, 16, v171
	v_and_b32_e32 v165, 0xffff0000, v171
	v_add_f32_e32 v160, v160, v164
	v_add_f32_e32 v161, v161, v165
	s_nop 0
	v_fma_f32 v157, v156, v161, -v163
	v_fma_f32 v156, v156, v160, -v162

.LBB0_934:
	s_or_b64 exec, exec, s[6:7]
	s_ashr_i32 s3, s8, 31
	v_mov_b32_e32 v161, s3
	v_or_b32_e32 v160, s8, v188
	v_lshlrev_b64 v[160:161], 11, v[160:161]
	v_lshl_add_u64 v[194:195], v[186:187], 0, v[160:161]
	global_load_dwordx4 v[124:127], v[128:129], off offset:512
	global_load_dwordx4 v[128:131], v[128:129], off offset:576
	v_mfma_f32_16x16x32_bf16 v[160:163], v[0:3], v[148:151], 0
	v_cvt_pk_bf16_f32 v155, v156, v157
	v_mfma_f32_16x16x32_bf16 v[164:167], v[16:19], v[148:151], 0
	s_nop 0
	v_mfma_f32_16x16x32_bf16 v[160:163], v[4:7], v[152:155], v[160:163]
	v_mfma_f32_16x16x32_bf16 v[168:171], v[24:27], v[148:151], 0
	v_mfma_f32_16x16x32_bf16 v[148:151], v[40:43], v[148:151], 0
	s_nop 5
	v_mul_f32_e64 v156, v12, v160
	v_mul_f32_e64 v157, v13, v161
	v_lshlrev_b32_e32 v160, 16, v144
	v_and_b32_e32 v161, 0xffff0000, v144
	v_mfma_f32_16x16x32_bf16 v[164:167], v[20:23], v[152:155], v[164:167]
	v_mul_f32_e64 v156, v156, v160
	v_mul_f32_e64 v157, v157, v161
	v_lshlrev_b32_e32 v160, 16, v146
	v_cvt_pk_bf16_f32 v144, v156, v157
	v_mfma_f32_16x16x32_bf16 v[168:171], v[28:31], v[152:155], v[168:171]
	v_lshlrev_b32_e32 v156, 16, v145
	v_and_b32_e32 v157, 0xffff0000, v145
	v_and_b32_e32 v161, 0xffff0000, v146
	v_mfma_f32_16x16x32_bf16 v[148:151], v[44:47], v[152:155], v[148:151]
	v_mul_f32_e64 v154, v14, v162
	v_mul_f32_e64 v155, v15, v163
	v_lshl_add_u64 v[152:153], v[194:195], 0, v[176:177]
	v_mul_f32_e32 v154, v154, v156
	v_mul_f32_e32 v155, v155, v157
	v_mul_f32_e32 v156, v8, v164
	v_mul_f32_e32 v157, v9, v165
	v_cvt_pk_bf16_f32 v145, v154, v155
	v_mul_f32_e32 v156, v156, v160
	v_mul_f32_e32 v157, v157, v161
	v_mul_f32_e32 v154, v10, v166
	v_mul_f32_e32 v155, v11, v167
	v_cvt_pk_bf16_f32 v146, v156, v157
	v_lshlrev_b32_e32 v156, 16, v147
	v_and_b32_e32 v157, 0xffff0000, v147
	v_mul_f32_e32 v154, v154, v156
	v_mul_f32_e32 v155, v155, v157
	s_nop 0
	v_cvt_pk_bf16_f32 v147, v154, v155
	global_store_dwordx4 v[152:153], v[144:147], off
	v_lshlrev_b32_e32 v154, 16, v140
	v_and_b32_e32 v155, 0xffff0000, v140
	v_mul_f32_e32 v146, v36, v168
	v_mul_f32_e32 v147, v37, v169
	v_mul_f32_e32 v144, v38, v170
	v_mul_f32_e32 v145, v39, v171
	v_mul_f32_e32 v146, v146, v154
	v_mul_f32_e32 v147, v147, v155
	s_nop 0
	v_cvt_pk_bf16_f32 v140, v146, v147
	v_lshlrev_b32_e32 v146, 16, v141
	v_and_b32_e32 v147, 0xffff0000, v141
	v_mul_f32_e32 v144, v144, v146
	v_mul_f32_e32 v145, v145, v147
	v_mul_f32_e32 v146, v32, v148
	v_mul_f32_e32 v147, v33, v149
	v_lshlrev_b32_e32 v148, 16, v142
	v_and_b32_e32 v149, 0xffff0000, v142
	v_mul_f32_e32 v146, v146, v148
	v_mul_f32_e32 v147, v147, v149
	v_cvt_pk_bf16_f32 v141, v144, v145
	v_mul_f32_e32 v144, v34, v150
	v_mul_f32_e32 v145, v35, v151
	v_cvt_pk_bf16_f32 v142, v146, v147
	v_lshlrev_b32_e32 v146, 16, v143
	v_and_b32_e32 v147, 0xffff0000, v143
	v_mul_f32_e32 v144, v144, v146
	v_mul_f32_e32 v145, v145, v147
	s_nop 0
	v_cvt_pk_bf16_f32 v143, v144, v145
	global_store_dwordx4 v[152:153], v[140:143], off offset:64
	s_and_saveexec_b64 s[6:7], s[36:37]
	s_xor_b64 s[6:7], exec, s[6:7]
	s_cbranch_execz .LBB0_936
	v_add_u32_e32 v140, 4, v158
	v_min_u32_e32 v140, s2, v140
	v_sub_u32_e64 v141, v158, 4 clamp
	v_sub_u32_e32 v140, v140, v141
	v_cvt_f32_i32_e32 v140, v140
	v_div_scale_f32 v141, s[10:11], v140, v140, 1.0
	v_rcp_f32_e32 v142, v141
	s_nop 0
	v_fma_f32 v143, -v141, v142, 1.0
	v_fmac_f32_e32 v142, v143, v142
	v_div_scale_f32 v143, vcc, 1.0, v140, 1.0
	v_mul_f32_e32 v144, v143, v142
	v_fma_f32 v145, -v141, v144, v143
	v_fmac_f32_e32 v144, v145, v142
	v_fma_f32 v141, -v141, v144, v143
	v_div_fmas_f32 v141, v141, v142, v144
	v_div_fixup_f32 v196, v141, v140, 1.0
	ds_read_b128 v[140:143], v244 offset:2112
	s_waitcnt lgkmcnt(0)
	v_lshlrev_b32_e32 v164, 16, v140
	v_and_b32_e32 v165, 0xffff0000, v140
	v_lshlrev_b32_e32 v166, 16, v141
	v_and_b32_e32 v167, 0xffff0000, v141
	v_lshlrev_b32_e32 v168, 16, v142
	v_and_b32_e32 v169, 0xffff0000, v142
	v_lshlrev_b32_e32 v170, 16, v143
	v_and_b32_e32 v171, 0xffff0000, v143
	ds_read_b128 v[140:143], v244 offset:2640
	v_add_f32_e32 v164, 0, v164
	v_add_f32_e32 v165, 0, v165
	s_waitcnt lgkmcnt(0)
	v_lshlrev_b32_e32 v172, 16, v140
	v_and_b32_e32 v173, 0xffff0000, v140
	v_lshlrev_b32_e32 v174, 16, v141
	v_and_b32_e32 v175, 0xffff0000, v141
	v_lshlrev_b32_e32 v198, 16, v142
	v_and_b32_e32 v199, 0xffff0000, v142
	v_lshlrev_b32_e32 v200, 16, v143
	v_and_b32_e32 v201, 0xffff0000, v143
	ds_read_b128 v[140:143], v244 offset:3168
	ds_read_b128 v[144:147], v244 offset:3696
	ds_read_b128 v[148:151], v244 offset:4224
	ds_read_b128 v[152:155], v244 offset:4752
	ds_read_b128 v[156:159], v244 offset:5280
	ds_read_b128 v[160:163], v244 offset:5808
	v_add_f32_e32 v164, v164, v172
	v_add_f32_e32 v165, v165, v173
	s_waitcnt lgkmcnt(5)
	v_lshlrev_b32_e32 v172, 16, v140
	v_and_b32_e32 v173, 0xffff0000, v140
	v_add_f32_e32 v164, v164, v172
	v_add_f32_e32 v165, v165, v173
	s_waitcnt lgkmcnt(4)
	v_lshlrev_b32_e32 v172, 16, v144
	v_and_b32_e32 v173, 0xffff0000, v144
	v_add_f32_e32 v164, v164, v172
	v_add_f32_e32 v165, v165, v173
	s_waitcnt lgkmcnt(3)
	v_lshlrev_b32_e32 v172, 16, v148
	v_and_b32_e32 v173, 0xffff0000, v148
	v_add_f32_e32 v164, v164, v172
	v_add_f32_e32 v165, v165, v173
	s_waitcnt lgkmcnt(2)
	v_lshlrev_b32_e32 v202, 16, v152
	v_and_b32_e32 v203, 0xffff0000, v152
	v_add_f32_e32 v164, v164, v202
	v_add_f32_e32 v165, v165, v203
	s_waitcnt lgkmcnt(1)
	v_lshlrev_b32_e32 v202, 16, v156
	v_and_b32_e32 v203, 0xffff0000, v156
	v_add_f32_e32 v164, v164, v202
	v_add_f32_e32 v165, v165, v203
	s_waitcnt lgkmcnt(0)
	v_lshlrev_b32_e32 v202, 16, v160
	v_and_b32_e32 v203, 0xffff0000, v160
	v_add_f32_e32 v164, v164, v202
	v_add_f32_e32 v165, v165, v203
	v_lshlrev_b32_e32 v144, 16, v145
	v_fma_f32 v164, v196, v164, -v172
	v_fma_f32 v165, v196, v165, -v173
	v_cvt_pk_bf16_f32 v140, v164, v165
	v_add_f32_e32 v164, 0, v166
	v_add_f32_e32 v165, 0, v167
	v_lshlrev_b32_e32 v166, 16, v141
	v_add_f32_e32 v164, v164, v174
	v_add_f32_e32 v165, v165, v175
	v_and_b32_e32 v167, 0xffff0000, v141
	v_add_f32_e32 v164, v164, v166
	v_add_f32_e32 v165, v165, v167
	v_and_b32_e32 v145, 0xffff0000, v145
	v_add_f32_e32 v144, v164, v144
	v_add_f32_e32 v145, v165, v145
	v_lshlrev_b32_e32 v148, 16, v149
	v_and_b32_e32 v149, 0xffff0000, v149
	v_add_f32_e32 v144, v144, v148
	v_add_f32_e32 v145, v145, v149
	v_lshlrev_b32_e32 v152, 16, v153
	v_and_b32_e32 v153, 0xffff0000, v153
	v_add_f32_e32 v144, v144, v152
	v_add_f32_e32 v145, v145, v153
	v_lshlrev_b32_e32 v152, 16, v157
	v_and_b32_e32 v153, 0xffff0000, v157
	v_add_f32_e32 v144, v144, v152
	v_add_f32_e32 v145, v145, v153
	v_lshlrev_b32_e32 v152, 16, v161
	v_and_b32_e32 v153, 0xffff0000, v161
	v_add_f32_e32 v144, v144, v152
	v_add_f32_e32 v145, v145, v153
	v_lshlrev_b32_e32 v152, 16, v154
	v_fma_f32 v144, v196, v144, -v148
	v_fma_f32 v145, v196, v145, -v149
	v_cvt_pk_bf16_f32 v141, v144, v145
	v_add_f32_e32 v144, 0, v168
	v_add_f32_e32 v145, 0, v169
	v_lshlrev_b32_e32 v148, 16, v142
	v_add_f32_e32 v144, v144, v198
	v_add_f32_e32 v145, v145, v199
	v_and_b32_e32 v149, 0xffff0000, v142
	v_add_f32_e32 v144, v144, v148
	v_add_f32_e32 v145, v145, v149
	v_lshlrev_b32_e32 v148, 16, v146
	v_and_b32_e32 v149, 0xffff0000, v146
	v_add_f32_e32 v144, v144, v148
	v_add_f32_e32 v145, v145, v149
	v_lshlrev_b32_e32 v148, 16, v150
	v_and_b32_e32 v149, 0xffff0000, v150
	v_add_f32_e32 v144, v144, v148
	v_add_f32_e32 v145, v145, v149
	v_and_b32_e32 v153, 0xffff0000, v154
	v_add_f32_e32 v144, v144, v152
	v_add_f32_e32 v145, v145, v153
	v_lshlrev_b32_e32 v152, 16, v158
	v_and_b32_e32 v153, 0xffff0000, v158
	v_add_f32_e32 v144, v144, v152
	v_add_f32_e32 v145, v145, v153
	v_lshlrev_b32_e32 v152, 16, v162
	v_and_b32_e32 v153, 0xffff0000, v162
	v_add_f32_e32 v144, v144, v152
	v_add_f32_e32 v145, v145, v153
	v_lshlrev_b32_e32 v146, 16, v147
	v_fma_f32 v144, v196, v144, -v148
	v_fma_f32 v145, v196, v145, -v149
	v_cvt_pk_bf16_f32 v142, v144, v145
	v_add_f32_e32 v144, 0, v170
	v_add_f32_e32 v145, 0, v171
	v_lshlrev_b32_e32 v148, 16, v143
	v_add_f32_e32 v144, v144, v200
	v_add_f32_e32 v145, v145, v201
	v_and_b32_e32 v149, 0xffff0000, v143
	v_add_f32_e32 v144, v144, v148
	v_add_f32_e32 v145, v145, v149
	v_and_b32_e32 v147, 0xffff0000, v147
	v_add_f32_e32 v144, v144, v146
	v_add_f32_e32 v145, v145, v147
	v_lshlrev_b32_e32 v146, 16, v151
	v_and_b32_e32 v147, 0xffff0000, v151
	v_add_f32_e32 v144, v144, v146
	v_add_f32_e32 v145, v145, v147
	v_lshlrev_b32_e32 v148, 16, v155
	v_and_b32_e32 v149, 0xffff0000, v155
	v_add_f32_e32 v144, v144, v148
	v_add_f32_e32 v145, v145, v149
	v_lshlrev_b32_e32 v148, 16, v159
	v_and_b32_e32 v149, 0xffff0000, v159
	v_add_f32_e32 v144, v144, v148
	v_add_f32_e32 v145, v145, v149
	v_lshlrev_b32_e32 v148, 16, v163
	v_and_b32_e32 v149, 0xffff0000, v163
	v_add_f32_e32 v144, v144, v148
	v_add_f32_e32 v145, v145, v149
	s_nop 0
	v_fma_f32 v144, v196, v144, -v146
	v_fma_f32 v145, v196, v145, -v147
	v_cvt_pk_bf16_f32 v143, v144, v145
	ds_read_b128 v[144:147], v244 offset:2176
	ds_read_b128 v[148:151], v244 offset:2704
	ds_read_b128 v[152:155], v244 offset:3232
	ds_read_b128 v[156:159], v244 offset:3760
	ds_read_b128 v[160:163], v244 offset:4288
	s_waitcnt lgkmcnt(4)
	v_lshlrev_b32_e32 v164, 16, v144
	v_and_b32_e32 v165, 0xffff0000, v144
	v_lshlrev_b32_e32 v144, 16, v145
	v_and_b32_e32 v145, 0xffff0000, v145
	v_add_f32_e32 v165, 0, v165
	s_waitcnt lgkmcnt(3)
	v_lshlrev_b32_e32 v166, 16, v148
	v_and_b32_e32 v167, 0xffff0000, v148
	v_lshlrev_b32_e32 v148, 16, v149
	v_and_b32_e32 v149, 0xffff0000, v149
	v_add_f32_e32 v164, v164, v166
	v_add_f32_e32 v165, v165, v167
	s_waitcnt lgkmcnt(2)
	v_lshlrev_b32_e32 v166, 16, v152
	v_and_b32_e32 v167, 0xffff0000, v152
	v_add_f32_e32 v144, v144, v148
	v_add_f32_e32 v145, v145, v149
	v_lshlrev_b32_e32 v148, 16, v153
	v_and_b32_e32 v149, 0xffff0000, v153
	v_lshlrev_b32_e32 v152, 16, v146
	v_and_b32_e32 v153, 0xffff0000, v146
	v_lshlrev_b32_e32 v146, 16, v147
	v_and_b32_e32 v147, 0xffff0000, v147
	v_add_f32_e32 v164, v164, v166
	v_add_f32_e32 v165, v165, v167
	s_waitcnt lgkmcnt(1)
	v_lshlrev_b32_e32 v166, 16, v156
	v_and_b32_e32 v167, 0xffff0000, v156
	v_add_f32_e32 v144, v144, v148
	v_add_f32_e32 v145, v145, v149
	v_lshlrev_b32_e32 v148, 16, v157
	v_and_b32_e32 v149, 0xffff0000, v157
	v_lshlrev_b32_e32 v156, 16, v150
	v_and_b32_e32 v157, 0xffff0000, v150
	v_lshlrev_b32_e32 v150, 16, v151
	v_and_b32_e32 v151, 0xffff0000, v151
	v_add_f32_e32 v152, v152, v156
	v_add_f32_e32 v153, v153, v157
	v_lshlrev_b32_e32 v156, 16, v154
	v_and_b32_e32 v157, 0xffff0000, v154
	v_add_f32_e32 v146, v146, v150
	v_add_f32_e32 v147, v147, v151
	v_lshlrev_b32_e32 v150, 16, v155
	v_and_b32_e32 v151, 0xffff0000, v155
	v_add_f32_e32 v152, v152, v156
	v_add_f32_e32 v153, v153, v157
	v_lshlrev_b32_e32 v156, 16, v158
	v_and_b32_e32 v157, 0xffff0000, v158
	v_add_f32_e32 v146, v146, v150
	v_add_f32_e32 v147, v147, v151
	v_lshlrev_b32_e32 v150, 16, v159
	v_and_b32_e32 v151, 0xffff0000, v159
	v_add_f32_e32 v164, v164, v166
	v_add_f32_e32 v165, v165, v167
	s_waitcnt lgkmcnt(0)
	v_lshlrev_b32_e32 v206, 16, v160
	v_and_b32_e32 v207, 0xffff0000, v160
	v_add_f32_e32 v148, v144, v148
	v_add_f32_e32 v149, v145, v149
	v_lshlrev_b32_e32 v144, 16, v161
	v_and_b32_e32 v145, 0xffff0000, v161
	v_add_f32_e32 v156, v152, v156
	v_add_f32_e32 v157, v153, v157
	v_lshlrev_b32_e32 v152, 16, v162
	v_and_b32_e32 v153, 0xffff0000, v162
	v_add_f32_e32 v150, v146, v150
	v_add_f32_e32 v151, v147, v151
	v_lshlrev_b32_e32 v146, 16, v163
	v_and_b32_e32 v147, 0xffff0000, v163
	v_add_f32_e32 v222, v164, v206
	v_add_f32_e32 v223, v165, v207
	v_add_f32_e32 v148, v148, v144
	v_add_f32_e32 v149, v149, v145
	v_add_f32_e32 v156, v156, v152
	v_add_f32_e32 v157, v157, v153
	v_add_f32_e32 v150, v150, v146
	v_add_f32_e32 v151, v151, v147
